# attention tile segments (guide 6.4/7.2): first LDS fragment reads lead each segment, next-tile prefetch block moved into their latency shadow
# speedup vs baseline: 1.0014x; 1.0014x over previous
.LBB0_1171:
	ds_read_b128 v[150:153], v144
	ds_read_b128 v[154:157], v144 offset:32
	ds_read_b128 v[158:161], v144 offset:64
	ds_read_b128 v[162:165], v144 offset:96
	ds_read_b128 v[166:169], v144 offset:128
	ds_read_b128 v[170:173], v144 offset:160
	ds_read_b128 v[174:177], v144 offset:6656
	ds_read_b128 v[178:181], v144 offset:6688
	s_add_i32 s23, s22, -1
	s_cmp_lt_u32 s23, s16
	s_cselect_b64 s[0:1], -1, 0
	s_cmp_ge_u32 s23, s16
	s_cbranch_scc1 .LBB0_1175
	v_lshl_add_u64 v[2:3], s[12:13], 0, v[128:129]
	v_add_co_u32_e32 v2, vcc, 0x4000, v2
	s_nop 1
	v_addc_co_u32_e32 v3, vcc, 0, v3, vcc
	global_load_dwordx4 v[80:83], v[2:3], off
	s_and_saveexec_b64 s[20:21], s[4:5]
	s_cbranch_execz .LBB0_1174
	v_lshl_add_u64 v[2:3], s[14:15], 0, v[128:129]
	v_add_co_u32_e32 v2, vcc, 0x2000, v2
	s_nop 1
	v_addc_co_u32_e32 v3, vcc, 0, v3, vcc
	global_load_dwordx4 v[84:87], v[2:3], off

.LBB0_1175:
	s_waitcnt lgkmcnt(7)
	v_mfma_f32_32x32x16_bf16 v[64:79], v[150:153], v[96:99], v[182:197]
	ds_read_b128 v[150:153], v144 offset:6720
	s_waitcnt lgkmcnt(7)
	v_mfma_f32_32x32x16_bf16 v[64:79], v[154:157], v[100:103], v[64:79]
	ds_read_b128 v[154:157], v144 offset:6752
	s_waitcnt lgkmcnt(7)
	v_mfma_f32_32x32x16_bf16 v[64:79], v[158:161], v[104:107], v[64:79]
	ds_read_b128 v[158:161], v144 offset:6784
	s_waitcnt lgkmcnt(7)
	v_mfma_f32_32x32x16_bf16 v[64:79], v[162:165], v[108:111], v[64:79]
	ds_read_b128 v[162:165], v144 offset:6816
	s_waitcnt lgkmcnt(7)
	v_mfma_f32_32x32x16_bf16 v[64:79], v[166:169], v[112:115], v[64:79]
	ds_read_b128 v[166:169], v145 offset:13312
	s_waitcnt lgkmcnt(7)
	v_mfma_f32_32x32x16_bf16 v[64:79], v[170:173], v[116:119], v[64:79]
	ds_read_b128 v[170:173], v145 offset:17920
	s_waitcnt lgkmcnt(7)
	v_mfma_f32_32x32x16_bf16 v[48:63], v[174:177], v[96:99], v[182:197]
	ds_read_b128 v[174:177], v145 offset:17952
	s_waitcnt lgkmcnt(7)
	v_mfma_f32_32x32x16_bf16 v[48:63], v[178:181], v[100:103], v[48:63]
	ds_read_b128 v[178:181], v145 offset:13344
	s_waitcnt lgkmcnt(7)
	v_mfma_f32_32x32x16_bf16 v[48:63], v[150:153], v[104:107], v[48:63]
	ds_read_b128 v[150:153], v145 offset:13376
	s_waitcnt lgkmcnt(7)
	v_mfma_f32_32x32x16_bf16 v[48:63], v[154:157], v[108:111], v[48:63]
	ds_read_b128 v[154:157], v145 offset:17984
	v_max3_f32 v214, v64, v65, v66
	v_max3_f32 v214, v214, v67, v68
	v_max3_f32 v214, v214, v69, v70
	v_max3_f32 v214, v214, v71, v72
	s_waitcnt lgkmcnt(7)
	v_mfma_f32_32x32x16_bf16 v[48:63], v[158:161], v[112:115], v[48:63]
	ds_read_b128 v[158:161], v145 offset:13408
	v_max3_f32 v214, v214, v73, v74
	v_max3_f32 v214, v214, v75, v76
	v_max3_f32 v214, v214, v77, v78
	v_max_f32_e32 v214, v214, v79
	s_waitcnt lgkmcnt(7)
	v_mfma_f32_32x32x16_bf16 v[48:63], v[162:165], v[116:119], v[48:63]
	ds_read_b128 v[162:165], v145 offset:18016
	s_nop 10
	v_max3_f32 v214, v214, v48, v49
	v_max3_f32 v214, v214, v50, v51
	v_max3_f32 v214, v214, v52, v53
	v_max3_f32 v214, v214, v54, v55
	v_max3_f32 v214, v214, v56, v57
	v_max3_f32 v214, v214, v58, v59
	v_max3_f32 v214, v214, v60, v61
	v_max3_f32 v214, v214, v62, v63
	v_mov_b32_e32 v215, v214
	v_mov_b32_e32 v216, v214
	s_nop 1
	v_permlane32_swap_b32_e32 v215, v216
	v_max3_f32 v214, v214, v215, v216
	v_cmp_lt_f32_e32 vcc, 4.0, v214
	s_cbranch_vccz .Lattn_fast_a
	v_max_f32_e32 v222, 0, v214
	v_exp_f32_e64 v224, -v222
	v_add_f32_e32 v0, v0, v222
	v_xor_b32_e32 v182, 0x80000000, v0
	v_mov_b32_e32 v183, v182
	v_mov_b32_e32 v184, v182
	v_mov_b32_e32 v185, v182
	v_mov_b32_e32 v186, v182
	v_mov_b32_e32 v187, v182
	v_mov_b32_e32 v188, v182
	v_mov_b32_e32 v189, v182
	v_mov_b32_e32 v190, v182
	v_mov_b32_e32 v191, v182
	v_mov_b32_e32 v192, v182
	v_mov_b32_e32 v193, v182
	v_mov_b32_e32 v194, v182
	v_mov_b32_e32 v195, v182
	v_mov_b32_e32 v196, v182
	v_mov_b32_e32 v197, v182
	v_pk_add_f32 v[64:65], v[64:65], v[222:223] op_sel_hi:[1,0] neg_lo:[0,1] neg_hi:[0,1]
	v_pk_add_f32 v[48:49], v[48:49], v[222:223] op_sel_hi:[1,0] neg_lo:[0,1] neg_hi:[0,1]
	v_pk_add_f32 v[66:67], v[66:67], v[222:223] op_sel_hi:[1,0] neg_lo:[0,1] neg_hi:[0,1]
	v_pk_add_f32 v[50:51], v[50:51], v[222:223] op_sel_hi:[1,0] neg_lo:[0,1] neg_hi:[0,1]
	v_pk_add_f32 v[68:69], v[68:69], v[222:223] op_sel_hi:[1,0] neg_lo:[0,1] neg_hi:[0,1]
	v_pk_add_f32 v[52:53], v[52:53], v[222:223] op_sel_hi:[1,0] neg_lo:[0,1] neg_hi:[0,1]
	v_pk_add_f32 v[70:71], v[70:71], v[222:223] op_sel_hi:[1,0] neg_lo:[0,1] neg_hi:[0,1]
	v_pk_add_f32 v[54:55], v[54:55], v[222:223] op_sel_hi:[1,0] neg_lo:[0,1] neg_hi:[0,1]
	v_pk_add_f32 v[72:73], v[72:73], v[222:223] op_sel_hi:[1,0] neg_lo:[0,1] neg_hi:[0,1]
	v_pk_add_f32 v[56:57], v[56:57], v[222:223] op_sel_hi:[1,0] neg_lo:[0,1] neg_hi:[0,1]
	v_pk_add_f32 v[74:75], v[74:75], v[222:223] op_sel_hi:[1,0] neg_lo:[0,1] neg_hi:[0,1]
	v_pk_add_f32 v[58:59], v[58:59], v[222:223] op_sel_hi:[1,0] neg_lo:[0,1] neg_hi:[0,1]
	v_pk_add_f32 v[76:77], v[76:77], v[222:223] op_sel_hi:[1,0] neg_lo:[0,1] neg_hi:[0,1]
	v_pk_add_f32 v[60:61], v[60:61], v[222:223] op_sel_hi:[1,0] neg_lo:[0,1] neg_hi:[0,1]
	v_pk_add_f32 v[78:79], v[78:79], v[222:223] op_sel_hi:[1,0] neg_lo:[0,1] neg_hi:[0,1]
	v_pk_add_f32 v[62:63], v[62:63], v[222:223] op_sel_hi:[1,0] neg_lo:[0,1] neg_hi:[0,1]
	v_mul_f32_e32 v148, v148, v224
	v_pk_mul_f32 v[46:47], v[46:47], v[224:225] op_sel_hi:[1,0]
	v_pk_mul_f32 v[44:45], v[44:45], v[224:225] op_sel_hi:[1,0]
	v_pk_mul_f32 v[42:43], v[42:43], v[224:225] op_sel_hi:[1,0]
	v_pk_mul_f32 v[40:41], v[40:41], v[224:225] op_sel_hi:[1,0]
	v_pk_mul_f32 v[38:39], v[38:39], v[224:225] op_sel_hi:[1,0]
	v_pk_mul_f32 v[36:37], v[36:37], v[224:225] op_sel_hi:[1,0]
	v_pk_mul_f32 v[34:35], v[34:35], v[224:225] op_sel_hi:[1,0]
	v_pk_mul_f32 v[32:33], v[32:33], v[224:225] op_sel_hi:[1,0]
	v_pk_mul_f32 v[30:31], v[30:31], v[224:225] op_sel_hi:[1,0]
	v_pk_mul_f32 v[28:29], v[28:29], v[224:225] op_sel_hi:[1,0]
	v_pk_mul_f32 v[26:27], v[26:27], v[224:225] op_sel_hi:[1,0]
	v_pk_mul_f32 v[24:25], v[24:25], v[224:225] op_sel_hi:[1,0]
	v_pk_mul_f32 v[22:23], v[22:23], v[224:225] op_sel_hi:[1,0]
	v_pk_mul_f32 v[20:21], v[20:21], v[224:225] op_sel_hi:[1,0]
	v_pk_mul_f32 v[18:19], v[18:19], v[224:225] op_sel_hi:[1,0]
	v_pk_mul_f32 v[16:17], v[16:17], v[224:225] op_sel_hi:[1,0]
.Lattn_fast_a:
	v_exp_f32_e32 v64, v64
	v_exp_f32_e32 v65, v65
	v_exp_f32_e32 v66, v66
	v_exp_f32_e32 v67, v67
	v_exp_f32_e32 v68, v68
	v_exp_f32_e32 v69, v69
	v_exp_f32_e32 v70, v70
	v_exp_f32_e32 v71, v71
	v_cvt_pk_bf16_f32 v230, v64, v65
	v_cvt_pk_bf16_f32 v231, v66, v67
	v_cvt_pk_bf16_f32 v232, v68, v69
	v_cvt_pk_bf16_f32 v233, v70, v71
	v_exp_f32_e32 v72, v72
	s_waitcnt lgkmcnt(7)
	v_mfma_f32_32x32x16_bf16 v[32:47], v[166:169], v[230:233], v[32:47]
	v_exp_f32_e32 v73, v73
	v_exp_f32_e32 v74, v74
	v_exp_f32_e32 v75, v75
	v_add_f32_e32 v218, v64, v65
	v_add_f32_e32 v219, v66, v67
	s_waitcnt lgkmcnt(6)
	v_mfma_f32_32x32x16_bf16 v[16:31], v[170:173], v[230:233], v[16:31]
	v_exp_f32_e32 v76, v76
	v_exp_f32_e32 v77, v77
	v_exp_f32_e32 v78, v78
	v_exp_f32_e32 v79, v79
	v_add_f32_e32 v220, v68, v69
	v_add_f32_e32 v221, v70, v71
	v_cvt_pk_bf16_f32 v234, v72, v73
	v_cvt_pk_bf16_f32 v235, v74, v75
	v_cvt_pk_bf16_f32 v236, v76, v77
	v_cvt_pk_bf16_f32 v237, v78, v79
	v_add_f32_e32 v218, v218, v72
	s_waitcnt lgkmcnt(5)
	v_mfma_f32_32x32x16_bf16 v[16:31], v[174:177], v[234:237], v[16:31]
	v_add_f32_e32 v218, v218, v73
	v_add_f32_e32 v219, v219, v74
	v_add_f32_e32 v219, v219, v75
	v_exp_f32_e32 v48, v48
	v_exp_f32_e32 v49, v49
	s_waitcnt lgkmcnt(4)
	v_mfma_f32_32x32x16_bf16 v[32:47], v[178:181], v[234:237], v[32:47]
	v_exp_f32_e32 v50, v50
	v_exp_f32_e32 v51, v51
	v_exp_f32_e32 v52, v52
	v_exp_f32_e32 v53, v53
	v_add_f32_e32 v220, v220, v76
	v_add_f32_e32 v220, v220, v77
	v_exp_f32_e32 v54, v54
	v_exp_f32_e32 v55, v55
	v_add_f32_e32 v221, v221, v78
	v_add_f32_e32 v221, v221, v79
	v_cvt_pk_bf16_f32 v230, v48, v49
	v_cvt_pk_bf16_f32 v231, v50, v51
	v_cvt_pk_bf16_f32 v232, v52, v53
	v_cvt_pk_bf16_f32 v233, v54, v55
	v_add_f32_e32 v218, v218, v48
	s_waitcnt lgkmcnt(3)
	v_mfma_f32_32x32x16_bf16 v[32:47], v[150:153], v[230:233], v[32:47]
	v_exp_f32_e32 v56, v56
	v_exp_f32_e32 v57, v57
	v_exp_f32_e32 v58, v58
	v_add_f32_e32 v218, v218, v49
	v_add_f32_e32 v219, v219, v50
	s_waitcnt lgkmcnt(2)
	v_mfma_f32_32x32x16_bf16 v[16:31], v[154:157], v[230:233], v[16:31]
	v_exp_f32_e32 v59, v59
	v_exp_f32_e32 v60, v60
	v_exp_f32_e32 v61, v61
	v_exp_f32_e32 v62, v62
	v_exp_f32_e32 v63, v63
	v_add_f32_e32 v219, v219, v51
	v_add_f32_e32 v220, v220, v52
	v_add_f32_e32 v220, v220, v53
	v_add_f32_e32 v221, v221, v54
	v_add_f32_e32 v221, v221, v55
	v_cvt_pk_bf16_f32 v234, v56, v57
	v_cvt_pk_bf16_f32 v235, v58, v59
	v_cvt_pk_bf16_f32 v236, v60, v61
	v_cvt_pk_bf16_f32 v237, v62, v63
	v_add_f32_e32 v218, v218, v56
	s_waitcnt lgkmcnt(1)
	v_mfma_f32_32x32x16_bf16 v[32:47], v[158:161], v[234:237], v[32:47]
	v_add_f32_e32 v218, v218, v57
	v_add_f32_e32 v219, v219, v58
	v_add_f32_e32 v219, v219, v59
	v_add_f32_e32 v220, v220, v60
	s_waitcnt lgkmcnt(0)
	v_mfma_f32_32x32x16_bf16 v[16:31], v[162:165], v[234:237], v[16:31]
	v_add_f32_e32 v220, v220, v61
	v_add_f32_e32 v221, v221, v62
	v_add_f32_e32 v221, v221, v63
	v_add_f32_e32 v218, v218, v219
	v_add_f32_e32 v220, v220, v221
	v_add_f32_e32 v218, v218, v220
	v_add_f32_e32 v148, v148, v218
	s_waitcnt vmcnt(1)
	ds_write_b128 v134, v[88:91] offset:22528
	s_and_saveexec_b64 s[20:21], s[4:5]
	v_add_u32_e32 v66, v147, v135
	ds_write_b128 v66, v[92:95] offset:22656
	s_or_b64 exec, exec, s[20:21]
	v_add_u32_e32 v66, 0x8800, v136
	s_cmp_ge_u32 s22, s16
	s_waitcnt vmcnt(0)
	ds_write2_b64 v66, v[124:125], v[126:127] offset0:128 offset1:130
	s_waitcnt lgkmcnt(0)
	s_barrier
	ds_read_b128 v[150:153], v144 offset:22528
	ds_read_b128 v[154:157], v144 offset:22560
	ds_read_b128 v[158:161], v144 offset:22592
	ds_read_b128 v[162:165], v144 offset:22624
	ds_read_b128 v[166:169], v144 offset:22656
	ds_read_b128 v[170:173], v144 offset:22688
	ds_read_b128 v[174:177], v144 offset:29184
	ds_read_b128 v[178:181], v144 offset:29216
	s_cbranch_scc1 .LBB0_1183
	v_lshl_add_u64 v[66:67], s[12:13], 0, v[128:129]
	v_add_co_u32_e32 v66, vcc, 0x6000, v66
	s_nop 1
	v_addc_co_u32_e32 v67, vcc, 0, v67, vcc
	global_load_dwordx4 v[88:91], v[66:67], off
	s_and_saveexec_b64 s[20:21], s[4:5]
	s_cbranch_execz .LBB0_1182
	v_lshl_add_u64 v[66:67], s[14:15], 0, v[128:129]
	v_add_co_u32_e32 v66, vcc, 0x3000, v66
	s_nop 1
	v_addc_co_u32_e32 v67, vcc, 0, v67, vcc
	global_load_dwordx4 v[92:95], v[66:67], off

.LBB0_1183:
	s_waitcnt lgkmcnt(7)
	v_mfma_f32_32x32x16_bf16 v[64:79], v[150:153], v[96:99], v[182:197]
	ds_read_b128 v[150:153], v144 offset:29248
	s_waitcnt lgkmcnt(7)
	v_mfma_f32_32x32x16_bf16 v[64:79], v[154:157], v[100:103], v[64:79]
	ds_read_b128 v[154:157], v144 offset:29280
	s_waitcnt lgkmcnt(7)
	v_mfma_f32_32x32x16_bf16 v[64:79], v[158:161], v[104:107], v[64:79]
	ds_read_b128 v[158:161], v144 offset:29312
	s_waitcnt lgkmcnt(7)
	v_mfma_f32_32x32x16_bf16 v[64:79], v[162:165], v[108:111], v[64:79]
	ds_read_b128 v[162:165], v144 offset:29344
	s_waitcnt lgkmcnt(7)
	v_mfma_f32_32x32x16_bf16 v[64:79], v[166:169], v[112:115], v[64:79]
	ds_read_b128 v[166:169], v145 offset:35840
	s_waitcnt lgkmcnt(7)
	v_mfma_f32_32x32x16_bf16 v[64:79], v[170:173], v[116:119], v[64:79]
	ds_read_b128 v[170:173], v145 offset:40448
	s_waitcnt lgkmcnt(7)
	v_mfma_f32_32x32x16_bf16 v[48:63], v[174:177], v[96:99], v[182:197]
	ds_read_b128 v[174:177], v145 offset:40480
	s_waitcnt lgkmcnt(7)
	v_mfma_f32_32x32x16_bf16 v[48:63], v[178:181], v[100:103], v[48:63]
	ds_read_b128 v[178:181], v145 offset:35872
	s_waitcnt lgkmcnt(7)
	v_mfma_f32_32x32x16_bf16 v[48:63], v[150:153], v[104:107], v[48:63]
	ds_read_b128 v[150:153], v145 offset:35904
	s_waitcnt lgkmcnt(7)
	v_mfma_f32_32x32x16_bf16 v[48:63], v[154:157], v[108:111], v[48:63]
	ds_read_b128 v[154:157], v145 offset:40512
	v_max3_f32 v214, v64, v65, v66
	v_max3_f32 v214, v214, v67, v68
	v_max3_f32 v214, v214, v69, v70
	v_max3_f32 v214, v214, v71, v72
	s_waitcnt lgkmcnt(7)
	v_mfma_f32_32x32x16_bf16 v[48:63], v[158:161], v[112:115], v[48:63]
	ds_read_b128 v[158:161], v145 offset:35936
	v_max3_f32 v214, v214, v73, v74
	v_max3_f32 v214, v214, v75, v76
	v_max3_f32 v214, v214, v77, v78
	v_max_f32_e32 v214, v214, v79
	s_waitcnt lgkmcnt(7)
	v_mfma_f32_32x32x16_bf16 v[48:63], v[162:165], v[116:119], v[48:63]
	ds_read_b128 v[162:165], v145 offset:40544
	s_nop 10
	v_max3_f32 v214, v214, v48, v49
	v_max3_f32 v214, v214, v50, v51
	v_max3_f32 v214, v214, v52, v53
	v_max3_f32 v214, v214, v54, v55
	v_max3_f32 v214, v214, v56, v57
	v_max3_f32 v214, v214, v58, v59
	v_max3_f32 v214, v214, v60, v61
	v_max3_f32 v214, v214, v62, v63
	v_mov_b32_e32 v215, v214
	v_mov_b32_e32 v216, v214
	s_nop 1
	v_permlane32_swap_b32_e32 v215, v216
	v_max3_f32 v214, v214, v215, v216
	v_cmp_lt_f32_e32 vcc, 4.0, v214
	s_cbranch_vccz .Lattn_fast_b
	v_max_f32_e32 v222, 0, v214
	v_exp_f32_e64 v224, -v222
	v_add_f32_e32 v0, v0, v222
	v_xor_b32_e32 v182, 0x80000000, v0
	v_mov_b32_e32 v183, v182
	v_mov_b32_e32 v184, v182
	v_mov_b32_e32 v185, v182
	v_mov_b32_e32 v186, v182
	v_mov_b32_e32 v187, v182
	v_mov_b32_e32 v188, v182
	v_mov_b32_e32 v189, v182
	v_mov_b32_e32 v190, v182
	v_mov_b32_e32 v191, v182
	v_mov_b32_e32 v192, v182
	v_mov_b32_e32 v193, v182
	v_mov_b32_e32 v194, v182
	v_mov_b32_e32 v195, v182
	v_mov_b32_e32 v196, v182
	v_mov_b32_e32 v197, v182
	v_pk_add_f32 v[64:65], v[64:65], v[222:223] op_sel_hi:[1,0] neg_lo:[0,1] neg_hi:[0,1]
	v_pk_add_f32 v[48:49], v[48:49], v[222:223] op_sel_hi:[1,0] neg_lo:[0,1] neg_hi:[0,1]
	v_pk_add_f32 v[66:67], v[66:67], v[222:223] op_sel_hi:[1,0] neg_lo:[0,1] neg_hi:[0,1]
	v_pk_add_f32 v[50:51], v[50:51], v[222:223] op_sel_hi:[1,0] neg_lo:[0,1] neg_hi:[0,1]
	v_pk_add_f32 v[68:69], v[68:69], v[222:223] op_sel_hi:[1,0] neg_lo:[0,1] neg_hi:[0,1]
	v_pk_add_f32 v[52:53], v[52:53], v[222:223] op_sel_hi:[1,0] neg_lo:[0,1] neg_hi:[0,1]
	v_pk_add_f32 v[70:71], v[70:71], v[222:223] op_sel_hi:[1,0] neg_lo:[0,1] neg_hi:[0,1]
	v_pk_add_f32 v[54:55], v[54:55], v[222:223] op_sel_hi:[1,0] neg_lo:[0,1] neg_hi:[0,1]
	v_pk_add_f32 v[72:73], v[72:73], v[222:223] op_sel_hi:[1,0] neg_lo:[0,1] neg_hi:[0,1]
	v_pk_add_f32 v[56:57], v[56:57], v[222:223] op_sel_hi:[1,0] neg_lo:[0,1] neg_hi:[0,1]
	v_pk_add_f32 v[74:75], v[74:75], v[222:223] op_sel_hi:[1,0] neg_lo:[0,1] neg_hi:[0,1]
	v_pk_add_f32 v[58:59], v[58:59], v[222:223] op_sel_hi:[1,0] neg_lo:[0,1] neg_hi:[0,1]
	v_pk_add_f32 v[76:77], v[76:77], v[222:223] op_sel_hi:[1,0] neg_lo:[0,1] neg_hi:[0,1]
	v_pk_add_f32 v[60:61], v[60:61], v[222:223] op_sel_hi:[1,0] neg_lo:[0,1] neg_hi:[0,1]
	v_pk_add_f32 v[78:79], v[78:79], v[222:223] op_sel_hi:[1,0] neg_lo:[0,1] neg_hi:[0,1]
	v_pk_add_f32 v[62:63], v[62:63], v[222:223] op_sel_hi:[1,0] neg_lo:[0,1] neg_hi:[0,1]
	v_mul_f32_e32 v148, v148, v224
	v_pk_mul_f32 v[46:47], v[46:47], v[224:225] op_sel_hi:[1,0]
	v_pk_mul_f32 v[44:45], v[44:45], v[224:225] op_sel_hi:[1,0]
	v_pk_mul_f32 v[42:43], v[42:43], v[224:225] op_sel_hi:[1,0]
	v_pk_mul_f32 v[40:41], v[40:41], v[224:225] op_sel_hi:[1,0]
	v_pk_mul_f32 v[38:39], v[38:39], v[224:225] op_sel_hi:[1,0]
	v_pk_mul_f32 v[36:37], v[36:37], v[224:225] op_sel_hi:[1,0]
	v_pk_mul_f32 v[34:35], v[34:35], v[224:225] op_sel_hi:[1,0]
	v_pk_mul_f32 v[32:33], v[32:33], v[224:225] op_sel_hi:[1,0]
	v_pk_mul_f32 v[30:31], v[30:31], v[224:225] op_sel_hi:[1,0]
	v_pk_mul_f32 v[28:29], v[28:29], v[224:225] op_sel_hi:[1,0]
	v_pk_mul_f32 v[26:27], v[26:27], v[224:225] op_sel_hi:[1,0]
	v_pk_mul_f32 v[24:25], v[24:25], v[224:225] op_sel_hi:[1,0]
	v_pk_mul_f32 v[22:23], v[22:23], v[224:225] op_sel_hi:[1,0]
	v_pk_mul_f32 v[20:21], v[20:21], v[224:225] op_sel_hi:[1,0]
	v_pk_mul_f32 v[18:19], v[18:19], v[224:225] op_sel_hi:[1,0]
	v_pk_mul_f32 v[16:17], v[16:17], v[224:225] op_sel_hi:[1,0]
